# v67 plus counted waits in the gate|up GEMM: peeled first K iteration skips the 8 SwiGLU epilogue stores
# baseline (speedup 1.0000x reference)
;     __device__ __forceinline__ bool next(int i, Unit& u) const { if (!StaticOrder::next(i / 3, u)) return false; u.aux = i % 3; return true; }
; #define PG8_STAGE(bufoff, gbase, voff) do { _Pragma("unroll") for (int _i = 0; _i < 2; ++_i) \
;         __builtin_amdgcn_global_load_lds((const unsigned*)((const char*)(gbase) + (voff)[_i]), (PG8_LAS unsigned*)(lds + (bufoff) + ldsw + _i * 8192), 16, 0, 0); } while (0)
; #define PG8_LDA(dst, b, h) do { _Pragma("unroll") for (int m = 0; m < 4; ++m) _Pragma("unroll") for (int k = 0; k < 2; ++k) dst[m][k] = *(const PG8_LAS bf16x8*)(lds + PG8_SA(b, h) + aoff + m * 2048 + k * 1024); } while (0)
; #define PG8_LDB(dst, b, h) do { _Pragma("unroll") for (int n = 0; n < 2; ++n) _Pragma("unroll") for (int k = 0; k < 2; ++k) dst[n][k] = *(const PG8_LAS bf16x8*)(lds + PG8_SB(b, h) + boff + n * 2048 + k * 1024); } while (0)
; #define PG8_MMA(ai, bj, At, Bt) do { __builtin_amdgcn_s_setprio(1); _Pragma("unroll") for (int m = 0; m < 4; ++m) _Pragma("unroll") for (int n = 0; n < 2; ++n) _Pragma("unroll") for (int k = 0; k < 2; ++k) \
;         acc[ai][bj][m][n] = __builtin_amdgcn_mfma_f32_16x16x32_bf16(Bt[n][k], At[m][k], acc[ai][bj][m][n], 0, 0, 0); __builtin_amdgcn_s_setprio(0); } while (0)
; #define PG8_WAIT_V(n) asm volatile("s_waitcnt vmcnt(" #n ")" ::: "memory")
; #define PG8_WAIT_L(n) asm volatile("s_waitcnt lgkmcnt(" #n ")" ::: "memory")
; template <class Epi, class Sched, bool ALIGN_EPI = false, bool SP2 = false>
; __device__ __forceinline__ void gemm_phase(PG8_LAS unsigned char* lds, const Gemm g, const Sched& S, const Epi& E) {
;     ...
;         const bool has_next = S.next(ui + 1, nxt);
;         const char* nA = cA; const char* nB = cB; if (has_next) S.bases(g, nxt, tstep, nA, nB);
;     ...
;             PG8_LDB(B0, 0, 0); PG8_LDB(B1, 0, 1); PG8_SCHED; PG8_LDA(At, 0, 0); PG8_STAGE(PG8_SA(1, 1), a1 + hstep, voffA);
;             PG8_WAIT_V(8); PG8_WAIT_L(0); PG8_BAR; PG8_MMA(0, 0, At, B0); PG8_MMA(0, 1, At, B1); PG8_BAR; PG8_SCHED;
;     ...
;         if (zero_acc) {
; #pragma unroll
;         for (int a = 0; a < 2; ++a)
; #pragma unroll
;             for (int b = 0; b < 2; ++b)
; #pragma unroll
;                 for (int m = 0; m < 4; ++m)
; #pragma unroll
;                     for (int n = 0; n < 2; ++n) acc[a][b][m][n] = (f32x4){0.f, 0.f, 0.f, 0.f};
;         }
;         cur = nxt; cA = nA; cB = nB; ++ui;
.LBB0_300:
	s_ashr_i32 s13, s12, 31
	s_lshl_b64 s[28:29], s[12:13], 20
	s_add_u32 s28, s43, s28
	s_addc_u32 s29, s44, s29
	s_ashr_i32 s11, s10, 31
	s_lshl_b64 s[30:31], s[10:11], 20
	s_add_u32 s30, s45, s30
	s_addc_u32 s31, s46, s31
	s_and_b64 s[40:41], s[0:1], exec
	s_cselect_b32 s11, s29, s37
	s_cselect_b32 s13, s28, s36
	s_cselect_b32 s56, s31, s39
	s_cselect_b32 s57, s30, s38
	s_add_u32 s36, s36, 0x80080
	s_addc_u32 s37, s37, 0
	s_add_u32 s58, s38, 0x100
	v_mov_b32_e32 v4, 0
	s_addc_u32 s59, s39, 0
	s_mov_b32 s60, -2
	v_mov_b32_e32 v5, v4
	v_mov_b32_e32 v6, v4
	v_mov_b32_e32 v7, v4
	v_mov_b32_e32 v12, v4
	v_mov_b32_e32 v13, v4
	v_mov_b32_e32 v14, v4
	v_mov_b32_e32 v15, v4
	v_mov_b32_e32 v20, v4
	v_mov_b32_e32 v21, v4
	v_mov_b32_e32 v22, v4
	v_mov_b32_e32 v23, v4
	v_mov_b32_e32 v28, v4
	v_mov_b32_e32 v29, v4
	v_mov_b32_e32 v30, v4
	v_mov_b32_e32 v31, v4
	v_mov_b32_e32 v36, v4
	v_mov_b32_e32 v37, v4
	v_mov_b32_e32 v38, v4
	v_mov_b32_e32 v39, v4
	v_mov_b32_e32 v44, v4
	v_mov_b32_e32 v45, v4
	v_mov_b32_e32 v46, v4
	v_mov_b32_e32 v47, v4
	v_mov_b32_e32 v52, v4
	v_mov_b32_e32 v53, v4
	v_mov_b32_e32 v54, v4
	v_mov_b32_e32 v55, v4
	v_mov_b32_e32 v60, v4
	v_mov_b32_e32 v61, v4
	v_mov_b32_e32 v62, v4
	v_mov_b32_e32 v63, v4
	v_mov_b32_e32 v8, v4
	v_mov_b32_e32 v9, v4
	v_mov_b32_e32 v10, v4
	v_mov_b32_e32 v11, v4
	v_mov_b32_e32 v16, v4
	v_mov_b32_e32 v17, v4
	v_mov_b32_e32 v18, v4
	v_mov_b32_e32 v19, v4
	v_mov_b32_e32 v24, v4
	v_mov_b32_e32 v25, v4
	v_mov_b32_e32 v26, v4
	v_mov_b32_e32 v27, v4
	v_mov_b32_e32 v32, v4
	v_mov_b32_e32 v33, v4
	v_mov_b32_e32 v34, v4
	v_mov_b32_e32 v35, v4
	v_mov_b32_e32 v40, v4
	v_mov_b32_e32 v41, v4
	v_mov_b32_e32 v42, v4
	v_mov_b32_e32 v43, v4
	v_mov_b32_e32 v48, v4
	v_mov_b32_e32 v49, v4
	v_mov_b32_e32 v50, v4
	v_mov_b32_e32 v51, v4
	v_mov_b32_e32 v56, v4
	v_mov_b32_e32 v57, v4
	v_mov_b32_e32 v58, v4
	v_mov_b32_e32 v59, v4
	v_mov_b32_e32 v64, v4
	v_mov_b32_e32 v65, v4
	v_mov_b32_e32 v66, v4
	v_mov_b32_e32 v67, v4
	v_mov_b32_e32 v68, v4
	v_mov_b32_e32 v69, v4
	v_mov_b32_e32 v70, v4
	v_mov_b32_e32 v71, v4
	v_mov_b32_e32 v76, v4
	v_mov_b32_e32 v77, v4
	v_mov_b32_e32 v78, v4
	v_mov_b32_e32 v79, v4
	v_mov_b32_e32 v84, v4
	v_mov_b32_e32 v85, v4
	v_mov_b32_e32 v86, v4
	v_mov_b32_e32 v87, v4
	v_mov_b32_e32 v92, v4
	v_mov_b32_e32 v93, v4
	v_mov_b32_e32 v94, v4
	v_mov_b32_e32 v95, v4
	v_mov_b32_e32 v100, v4
	v_mov_b32_e32 v101, v4
	v_mov_b32_e32 v102, v4
	v_mov_b32_e32 v103, v4
	v_mov_b32_e32 v108, v4
	v_mov_b32_e32 v109, v4
	v_mov_b32_e32 v110, v4
	v_mov_b32_e32 v111, v4
	v_mov_b32_e32 v116, v4
	v_mov_b32_e32 v117, v4
	v_mov_b32_e32 v118, v4
	v_mov_b32_e32 v119, v4
	v_mov_b32_e32 v124, v4
	v_mov_b32_e32 v125, v4
	v_mov_b32_e32 v126, v4
	v_mov_b32_e32 v127, v4
	v_mov_b32_e32 v72, v4
	v_mov_b32_e32 v73, v4
	v_mov_b32_e32 v74, v4
	v_mov_b32_e32 v75, v4
	v_mov_b32_e32 v80, v4
	v_mov_b32_e32 v81, v4
	v_mov_b32_e32 v82, v4
	v_mov_b32_e32 v83, v4
	v_mov_b32_e32 v88, v4
	v_mov_b32_e32 v89, v4
	v_mov_b32_e32 v90, v4
	v_mov_b32_e32 v91, v4
	v_mov_b32_e32 v96, v4
	v_mov_b32_e32 v97, v4
	v_mov_b32_e32 v98, v4
	v_mov_b32_e32 v99, v4
	v_mov_b32_e32 v104, v4
	v_mov_b32_e32 v105, v4
	v_mov_b32_e32 v106, v4
	v_mov_b32_e32 v107, v4
	v_mov_b32_e32 v112, v4
	v_mov_b32_e32 v113, v4
	v_mov_b32_e32 v114, v4
	v_mov_b32_e32 v115, v4
	v_mov_b32_e32 v120, v4
	v_mov_b32_e32 v121, v4
	v_mov_b32_e32 v122, v4
	v_mov_b32_e32 v123, v4
	v_mov_b32_e32 v128, v4
	v_mov_b32_e32 v129, v4
	v_mov_b32_e32 v130, v4
	v_mov_b32_e32 v131, v4
	v_add_u32_e32 v249, 0x10000, v150
	s_cmp_eq_u32 s32, 0
	s_cbranch_scc1 .LBB0_301
	s_add_u32 s38, s36, 0xfff80080
	s_addc_u32 s39, s37, -1
	s_add_i32 s61, 0, 0x10000
	s_cmp_eq_u32 s60, 28
	s_cselect_b32 s41, s11, s39
	s_cselect_b32 s40, s13, s38
	s_cselect_b32 s39, s56, s59
	s_cselect_b32 s38, s57, s58
	s_add_i32 s64, 0, 0x14000
	ds_read_b128 v[142:145], v249
	ds_read_b128 v[146:149], v249 offset:1024
	ds_read_b128 v[154:157], v249 offset:2048
	ds_read_b128 v[158:161], v249 offset:3072
	ds_read_b128 v[174:177], v249 offset:16384
	ds_read_b128 v[178:181], v249 offset:17408
	ds_read_b128 v[204:207], v249 offset:18432
	ds_read_b128 v[208:211], v249 offset:19456
	s_add_i32 m0, s47, 0xc000
	ds_read_b128 v[212:215], v153
	ds_read_b128 v[216:219], v153 offset:1024
	ds_read_b128 v[220:223], v153 offset:2048
	ds_read_b128 v[224:227], v153 offset:3072
	ds_read_b128 v[228:231], v153 offset:4096
	ds_read_b128 v[232:235], v153 offset:5120
	ds_read_b128 v[236:239], v153 offset:6144
	ds_read_b128 v[240:243], v153 offset:7168
	global_load_lds_dwordx4 v138, s[36:37]
	s_add_i32 m0, s47, 0xe000
	s_nop 0
	global_load_lds_dwordx4 v140, s[36:37]
	s_waitcnt vmcnt(16) lgkmcnt(0)
	s_setprio 0
	s_barrier
; #define PG8_STAGE(bufoff, gbase, voff) do { _Pragma("unroll") for (int _i = 0; _i < 2; ++_i) \
;         __builtin_amdgcn_global_load_lds((const unsigned*)((const char*)(gbase) + (voff)[_i]), (PG8_LAS unsigned*)(lds + (bufoff) + ldsw + _i * 8192), 16, 0, 0); } while (0)
; #define PG8_LDA(dst, b, h) do { _Pragma("unroll") for (int m = 0; m < 4; ++m) _Pragma("unroll") for (int k = 0; k < 2; ++k) dst[m][k] = *(const PG8_LAS bf16x8*)(lds + PG8_SA(b, h) + aoff + m * 2048 + k * 1024); } while (0)
; #define PG8_MMA(ai, bj, At, Bt) do { __builtin_amdgcn_s_setprio(1); _Pragma("unroll") for (int m = 0; m < 4; ++m) _Pragma("unroll") for (int n = 0; n < 2; ++n) _Pragma("unroll") for (int k = 0; k < 2; ++k) \
;         acc[ai][bj][m][n] = __builtin_amdgcn_mfma_f32_16x16x32_bf16(Bt[n][k], At[m][k], acc[ai][bj][m][n], 0, 0, 0); __builtin_amdgcn_s_setprio(0); } while (0)
; #define PG8_WAIT_V(n) asm volatile("s_waitcnt vmcnt(" #n ")" ::: "memory")
; #define PG8_WAIT_L(n) asm volatile("s_waitcnt lgkmcnt(" #n ")" ::: "memory")
; #define PG8_BAR __builtin_amdgcn_s_barrier()
; #define PG8_SCHED __builtin_amdgcn_sched_barrier(0)
; template <class Epi, class Sched, bool ALIGN_EPI = false, bool SP2 = false>
; __device__ __forceinline__ void gemm_phase(PG8_LAS unsigned char* lds, const Gemm g, const Sched& S, const Epi& E) {
;     ...
;             PG8_WAIT_V(8); PG8_WAIT_L(0); PG8_BAR; PG8_MMA(0, 0, At, B0); PG8_MMA(0, 1, At, B1); PG8_BAR; PG8_SCHED;
;             PG8_LDA(At, 0, 1); PG8_STAGE(PG8_SB(0, 0), b2, voffB); PG8_STAGE(PG8_SB(0, 1), b2 + hstep, voffB); PG8_STAGE(PG8_SA(0, 0), a2, voffA);
;             PG8_WAIT_V(8); PG8_WAIT_L(0); PG8_BAR; PG8_MMA(1, 0, At, B0); PG8_MMA(1, 1, At, B1); PG8_BAR; PG8_SCHED;
	v_mfma_f32_16x16x32_bf16 v[128:131], v[142:145], v[212:215], v[128:131]
	v_mfma_f32_16x16x32_bf16 v[120:123], v[154:157], v[212:215], v[120:123]
	v_mfma_f32_16x16x32_bf16 v[112:115], v[142:145], v[220:223], v[112:115]
	v_mfma_f32_16x16x32_bf16 v[104:107], v[154:157], v[220:223], v[104:107]
	v_mfma_f32_16x16x32_bf16 v[96:99], v[142:145], v[228:231], v[96:99]
	v_mfma_f32_16x16x32_bf16 v[88:91], v[154:157], v[228:231], v[88:91]
	v_mfma_f32_16x16x32_bf16 v[80:83], v[142:145], v[236:239], v[80:83]
	v_mfma_f32_16x16x32_bf16 v[72:75], v[154:157], v[236:239], v[72:75]
	v_mfma_f32_16x16x32_bf16 v[128:131], v[146:149], v[216:219], v[128:131]
	v_mfma_f32_16x16x32_bf16 v[120:123], v[158:161], v[216:219], v[120:123]
	v_mfma_f32_16x16x32_bf16 v[112:115], v[146:149], v[224:227], v[112:115]
	v_mfma_f32_16x16x32_bf16 v[104:107], v[158:161], v[224:227], v[104:107]
	v_mfma_f32_16x16x32_bf16 v[96:99], v[146:149], v[232:235], v[96:99]
	v_mfma_f32_16x16x32_bf16 v[88:91], v[158:161], v[232:235], v[88:91]
	v_mfma_f32_16x16x32_bf16 v[80:83], v[146:149], v[240:243], v[80:83]
	v_mfma_f32_16x16x32_bf16 v[72:75], v[158:161], v[240:243], v[72:75]
	v_mfma_f32_16x16x32_bf16 v[124:127], v[174:177], v[212:215], v[124:127]
	v_mfma_f32_16x16x32_bf16 v[116:119], v[204:207], v[212:215], v[116:119]
	v_mfma_f32_16x16x32_bf16 v[108:111], v[174:177], v[220:223], v[108:111]
	v_mfma_f32_16x16x32_bf16 v[100:103], v[204:207], v[220:223], v[100:103]
	v_mfma_f32_16x16x32_bf16 v[92:95], v[174:177], v[228:231], v[92:95]
	v_mfma_f32_16x16x32_bf16 v[84:87], v[204:207], v[228:231], v[84:87]
	v_mfma_f32_16x16x32_bf16 v[76:79], v[174:177], v[236:239], v[76:79]
	v_mfma_f32_16x16x32_bf16 v[68:71], v[204:207], v[236:239], v[68:71]
	v_mfma_f32_16x16x32_bf16 v[124:127], v[178:181], v[216:219], v[124:127]
	v_mfma_f32_16x16x32_bf16 v[116:119], v[208:211], v[216:219], v[116:119]
	v_mfma_f32_16x16x32_bf16 v[108:111], v[178:181], v[224:227], v[108:111]
	v_mfma_f32_16x16x32_bf16 v[100:103], v[208:211], v[224:227], v[100:103]
	v_mfma_f32_16x16x32_bf16 v[92:95], v[178:181], v[232:235], v[92:95]
	v_mfma_f32_16x16x32_bf16 v[84:87], v[208:211], v[232:235], v[84:87]
	v_mfma_f32_16x16x32_bf16 v[76:79], v[178:181], v[240:243], v[76:79]
	v_mfma_f32_16x16x32_bf16 v[68:71], v[208:211], v[240:243], v[68:71]
	s_setprio 3
	s_barrier
	s_add_i32 s61, s61, s42
	s_mov_b32 m0, s61
	ds_read_b128 v[212:215], v153 offset:16384
	ds_read_b128 v[216:219], v153 offset:17408
	ds_read_b128 v[220:223], v153 offset:18432
	ds_read_b128 v[224:227], v153 offset:19456
	ds_read_b128 v[228:231], v153 offset:20480
	ds_read_b128 v[232:235], v153 offset:21504
	ds_read_b128 v[236:239], v153 offset:22528
	ds_read_b128 v[240:243], v153 offset:23552
	global_load_lds_dwordx4 v2, s[38:39]
	s_add_i32 m0, s61, 0x2000
	s_add_u32 s62, s38, 0x80000
	s_addc_u32 s63, s39, 0
	s_add_i32 s61, s64, s42
	global_load_lds_dwordx4 v132, s[38:39]
	s_mov_b32 m0, s61
	s_nop 0
	global_load_lds_dwordx4 v2, s[62:63]
	s_add_i32 m0, s61, 0x2000
	s_nop 0
	global_load_lds_dwordx4 v132, s[62:63]
	s_mov_b32 m0, s47
	s_nop 0
	global_load_lds_dwordx4 v136, s[40:41]
	s_mov_b32 m0, s48
	s_nop 0
	global_load_lds_dwordx4 v134, s[40:41]
	s_waitcnt vmcnt(16) lgkmcnt(0)
	s_setprio 0
	s_barrier
	v_mfma_f32_16x16x32_bf16 v[64:67], v[142:145], v[212:215], v[64:67]
	v_mfma_f32_16x16x32_bf16 v[56:59], v[154:157], v[212:215], v[56:59]
	v_mfma_f32_16x16x32_bf16 v[48:51], v[142:145], v[220:223], v[48:51]
	v_mfma_f32_16x16x32_bf16 v[40:43], v[154:157], v[220:223], v[40:43]
	v_mfma_f32_16x16x32_bf16 v[32:35], v[142:145], v[228:231], v[32:35]
	v_mfma_f32_16x16x32_bf16 v[24:27], v[154:157], v[228:231], v[24:27]
	v_mfma_f32_16x16x32_bf16 v[16:19], v[142:145], v[236:239], v[16:19]
	v_mfma_f32_16x16x32_bf16 v[8:11], v[154:157], v[236:239], v[8:11]
	v_mfma_f32_16x16x32_bf16 v[64:67], v[146:149], v[216:219], v[64:67]
	v_mfma_f32_16x16x32_bf16 v[56:59], v[158:161], v[216:219], v[56:59]
	v_mfma_f32_16x16x32_bf16 v[48:51], v[146:149], v[224:227], v[48:51]
	v_mfma_f32_16x16x32_bf16 v[40:43], v[158:161], v[224:227], v[40:43]
	v_mfma_f32_16x16x32_bf16 v[32:35], v[146:149], v[232:235], v[32:35]
	v_mfma_f32_16x16x32_bf16 v[24:27], v[158:161], v[232:235], v[24:27]
	v_mfma_f32_16x16x32_bf16 v[16:19], v[146:149], v[240:243], v[16:19]
	v_mfma_f32_16x16x32_bf16 v[8:11], v[158:161], v[240:243], v[8:11]
	v_mfma_f32_16x16x32_bf16 v[60:63], v[174:177], v[212:215], v[60:63]
	v_mfma_f32_16x16x32_bf16 v[52:55], v[204:207], v[212:215], v[52:55]
	v_mfma_f32_16x16x32_bf16 v[44:47], v[174:177], v[220:223], v[44:47]
	v_mfma_f32_16x16x32_bf16 v[36:39], v[204:207], v[220:223], v[36:39]
	v_mfma_f32_16x16x32_bf16 v[28:31], v[174:177], v[228:231], v[28:31]
	v_mfma_f32_16x16x32_bf16 v[20:23], v[204:207], v[228:231], v[20:23]
	v_mfma_f32_16x16x32_bf16 v[12:15], v[174:177], v[236:239], v[12:15]
	v_mfma_f32_16x16x32_bf16 v[4:7], v[204:207], v[236:239], v[4:7]
	v_mfma_f32_16x16x32_bf16 v[60:63], v[178:181], v[216:219], v[60:63]
	v_mfma_f32_16x16x32_bf16 v[52:55], v[208:211], v[216:219], v[52:55]
	v_mfma_f32_16x16x32_bf16 v[44:47], v[178:181], v[224:227], v[44:47]
	v_mfma_f32_16x16x32_bf16 v[36:39], v[208:211], v[224:227], v[36:39]
	v_mfma_f32_16x16x32_bf16 v[28:31], v[178:181], v[232:235], v[28:31]
	v_mfma_f32_16x16x32_bf16 v[20:23], v[208:211], v[232:235], v[20:23]
	v_mfma_f32_16x16x32_bf16 v[12:15], v[178:181], v[240:243], v[12:15]
	v_mfma_f32_16x16x32_bf16 v[4:7], v[208:211], v[240:243], v[4:7]
	s_setprio 3
	s_barrier
; #define PG8_STAGE(bufoff, gbase, voff) do { _Pragma("unroll") for (int _i = 0; _i < 2; ++_i) \
;         __builtin_amdgcn_global_load_lds((const unsigned*)((const char*)(gbase) + (voff)[_i]), (PG8_LAS unsigned*)(lds + (bufoff) + ldsw + _i * 8192), 16, 0, 0); } while (0)
; #define PG8_LDA(dst, b, h) do { _Pragma("unroll") for (int m = 0; m < 4; ++m) _Pragma("unroll") for (int k = 0; k < 2; ++k) dst[m][k] = *(const PG8_LAS bf16x8*)(lds + PG8_SA(b, h) + aoff + m * 2048 + k * 1024); } while (0)
; #define PG8_LDB(dst, b, h) do { _Pragma("unroll") for (int n = 0; n < 2; ++n) _Pragma("unroll") for (int k = 0; k < 2; ++k) dst[n][k] = *(const PG8_LAS bf16x8*)(lds + PG8_SB(b, h) + boff + n * 2048 + k * 1024); } while (0)
; #define PG8_MMA(ai, bj, At, Bt) do { __builtin_amdgcn_s_setprio(1); _Pragma("unroll") for (int m = 0; m < 4; ++m) _Pragma("unroll") for (int n = 0; n < 2; ++n) _Pragma("unroll") for (int k = 0; k < 2; ++k) \
;         acc[ai][bj][m][n] = __builtin_amdgcn_mfma_f32_16x16x32_bf16(Bt[n][k], At[m][k], acc[ai][bj][m][n], 0, 0, 0); __builtin_amdgcn_s_setprio(0); } while (0)
; #define PG8_WAIT_V(n) asm volatile("s_waitcnt vmcnt(" #n ")" ::: "memory")
; #define PG8_WAIT_L(n) asm volatile("s_waitcnt lgkmcnt(" #n ")" ::: "memory")
; #define PG8_BAR __builtin_amdgcn_s_barrier()
; #define PG8_SCHED __builtin_amdgcn_sched_barrier(0)
; template <class Epi, class Sched, bool ALIGN_EPI = false, bool SP2 = false>
; __device__ __forceinline__ void gemm_phase(PG8_LAS unsigned char* lds, const Gemm g, const Sched& S, const Epi& E) {
;     ...
;             PG8_LDB(B0, 1, 0); PG8_LDB(B1, 1, 1); PG8_SCHED; PG8_LDA(At, 1, 0); PG8_STAGE(PG8_SA(0, 1), a2 + hstep, voffA);
;             PG8_WAIT_V(8); PG8_WAIT_L(0); PG8_BAR; PG8_MMA(0, 0, At, B0); PG8_MMA(0, 1, At, B1); PG8_BAR; PG8_SCHED;
;             PG8_LDA(At, 1, 1); PG8_STAGE(PG8_SB(1, 0), b3, voffB); PG8_STAGE(PG8_SB(1, 1), b3 + hstep, voffB); PG8_STAGE(PG8_SA(1, 0), a3, voffA);
;             PG8_WAIT_V(8); PG8_WAIT_L(0); PG8_BAR; PG8_MMA(1, 0, At, B0); PG8_MMA(1, 1, At, B1); PG8_BAR; PG8_SCHED;
	s_add_i32 s61, 0, 0x18000
	s_add_i32 s62, 0, 0x1c000
	ds_read_b128 v[142:145], v249 offset:32768
	ds_read_b128 v[146:149], v249 offset:33792
	ds_read_b128 v[154:157], v249 offset:34816
	ds_read_b128 v[158:161], v249 offset:35840
	ds_read_b128 v[174:177], v249 offset:49152
	ds_read_b128 v[178:181], v249 offset:50176
	ds_read_b128 v[204:207], v249 offset:51200
	ds_read_b128 v[208:211], v249 offset:52224
	s_add_u32 s100, s40, 0x80
	s_addc_u32 s101, s41, 0
	s_add_u32 s40, s40, 0x80000
	s_addc_u32 s41, s41, 0
	s_mov_b32 m0, s49
	ds_read_b128 v[212:215], v153 offset:32768
	ds_read_b128 v[216:219], v153 offset:33792
	ds_read_b128 v[220:223], v153 offset:34816
	ds_read_b128 v[224:227], v153 offset:35840
	ds_read_b128 v[228:231], v153 offset:36864
	ds_read_b128 v[232:235], v153 offset:37888
	ds_read_b128 v[236:239], v153 offset:38912
	ds_read_b128 v[240:243], v153 offset:39936
	global_load_lds_dwordx4 v136, s[40:41]
	s_mov_b32 m0, s50
	s_nop 0
	global_load_lds_dwordx4 v134, s[40:41]
	s_waitcnt vmcnt(8) lgkmcnt(0)
	s_setprio 0
	s_barrier
	v_mfma_f32_16x16x32_bf16 v[128:131], v[142:145], v[212:215], v[128:131]
	v_mfma_f32_16x16x32_bf16 v[120:123], v[154:157], v[212:215], v[120:123]
	v_mfma_f32_16x16x32_bf16 v[112:115], v[142:145], v[220:223], v[112:115]
	v_mfma_f32_16x16x32_bf16 v[104:107], v[154:157], v[220:223], v[104:107]
	v_mfma_f32_16x16x32_bf16 v[96:99], v[142:145], v[228:231], v[96:99]
	v_mfma_f32_16x16x32_bf16 v[88:91], v[154:157], v[228:231], v[88:91]
	v_mfma_f32_16x16x32_bf16 v[80:83], v[142:145], v[236:239], v[80:83]
	v_mfma_f32_16x16x32_bf16 v[72:75], v[154:157], v[236:239], v[72:75]
	v_mfma_f32_16x16x32_bf16 v[128:131], v[146:149], v[216:219], v[128:131]
	v_mfma_f32_16x16x32_bf16 v[120:123], v[158:161], v[216:219], v[120:123]
	v_mfma_f32_16x16x32_bf16 v[112:115], v[146:149], v[224:227], v[112:115]
	v_mfma_f32_16x16x32_bf16 v[104:107], v[158:161], v[224:227], v[104:107]
	v_mfma_f32_16x16x32_bf16 v[96:99], v[146:149], v[232:235], v[96:99]
	v_mfma_f32_16x16x32_bf16 v[88:91], v[158:161], v[232:235], v[88:91]
	v_mfma_f32_16x16x32_bf16 v[80:83], v[146:149], v[240:243], v[80:83]
	v_mfma_f32_16x16x32_bf16 v[72:75], v[158:161], v[240:243], v[72:75]
	v_mfma_f32_16x16x32_bf16 v[124:127], v[174:177], v[212:215], v[124:127]
	v_mfma_f32_16x16x32_bf16 v[116:119], v[204:207], v[212:215], v[116:119]
	v_mfma_f32_16x16x32_bf16 v[108:111], v[174:177], v[220:223], v[108:111]
	v_mfma_f32_16x16x32_bf16 v[100:103], v[204:207], v[220:223], v[100:103]
	v_mfma_f32_16x16x32_bf16 v[92:95], v[174:177], v[228:231], v[92:95]
	v_mfma_f32_16x16x32_bf16 v[84:87], v[204:207], v[228:231], v[84:87]
	v_mfma_f32_16x16x32_bf16 v[76:79], v[174:177], v[236:239], v[76:79]
	v_mfma_f32_16x16x32_bf16 v[68:71], v[204:207], v[236:239], v[68:71]
	v_mfma_f32_16x16x32_bf16 v[124:127], v[178:181], v[216:219], v[124:127]
	v_mfma_f32_16x16x32_bf16 v[116:119], v[208:211], v[216:219], v[116:119]
	v_mfma_f32_16x16x32_bf16 v[108:111], v[178:181], v[224:227], v[108:111]
	v_mfma_f32_16x16x32_bf16 v[100:103], v[208:211], v[224:227], v[100:103]
	v_mfma_f32_16x16x32_bf16 v[92:95], v[178:181], v[232:235], v[92:95]
	v_mfma_f32_16x16x32_bf16 v[84:87], v[208:211], v[232:235], v[84:87]
	v_mfma_f32_16x16x32_bf16 v[76:79], v[178:181], v[240:243], v[76:79]
	v_mfma_f32_16x16x32_bf16 v[68:71], v[208:211], v[240:243], v[68:71]
	s_setprio 3
	s_barrier
	s_add_i32 s40, s61, s42
	s_add_i32 m0, s40, 0xffffff80
	ds_read_b128 v[212:215], v153 offset:49152
	ds_read_b128 v[216:219], v153 offset:50176
	ds_read_b128 v[220:223], v153 offset:51200
	ds_read_b128 v[224:227], v153 offset:52224
	ds_read_b128 v[228:231], v153 offset:53248
	ds_read_b128 v[232:235], v153 offset:54272
	ds_read_b128 v[236:239], v153 offset:55296
	ds_read_b128 v[240:243], v153 offset:56320
	global_load_lds_dwordx4 v2, s[38:39] offset:128
	s_add_i32 m0, s40, 0x1f80
	s_add_i32 s40, s62, s42
	global_load_lds_dwordx4 v132, s[38:39] offset:128
	s_add_u32 s38, s38, 0x80080
	s_addc_u32 s39, s39, 0
	s_mov_b32 m0, s40
	s_nop 0
	global_load_lds_dwordx4 v2, s[38:39]
	s_add_i32 m0, s40, 0x2000
	s_nop 0
	global_load_lds_dwordx4 v132, s[38:39]
	s_mov_b32 m0, s51
	s_nop 0
	global_load_lds_dwordx4 v136, s[100:101]
	s_mov_b32 m0, s53
	s_nop 0
	global_load_lds_dwordx4 v134, s[100:101]
	s_waitcnt vmcnt(8) lgkmcnt(0)
	s_setprio 0
	s_barrier
	v_mfma_f32_16x16x32_bf16 v[64:67], v[142:145], v[212:215], v[64:67]
	v_mfma_f32_16x16x32_bf16 v[56:59], v[154:157], v[212:215], v[56:59]
	v_mfma_f32_16x16x32_bf16 v[48:51], v[142:145], v[220:223], v[48:51]
	v_mfma_f32_16x16x32_bf16 v[40:43], v[154:157], v[220:223], v[40:43]
	v_mfma_f32_16x16x32_bf16 v[32:35], v[142:145], v[228:231], v[32:35]
	v_mfma_f32_16x16x32_bf16 v[24:27], v[154:157], v[228:231], v[24:27]
	v_mfma_f32_16x16x32_bf16 v[16:19], v[142:145], v[236:239], v[16:19]
	v_mfma_f32_16x16x32_bf16 v[8:11], v[154:157], v[236:239], v[8:11]
	v_mfma_f32_16x16x32_bf16 v[64:67], v[146:149], v[216:219], v[64:67]
	v_mfma_f32_16x16x32_bf16 v[56:59], v[158:161], v[216:219], v[56:59]
	v_mfma_f32_16x16x32_bf16 v[48:51], v[146:149], v[224:227], v[48:51]
	v_mfma_f32_16x16x32_bf16 v[40:43], v[158:161], v[224:227], v[40:43]
	v_mfma_f32_16x16x32_bf16 v[32:35], v[146:149], v[232:235], v[32:35]
	v_mfma_f32_16x16x32_bf16 v[24:27], v[158:161], v[232:235], v[24:27]
	v_mfma_f32_16x16x32_bf16 v[16:19], v[146:149], v[240:243], v[16:19]
	v_mfma_f32_16x16x32_bf16 v[8:11], v[158:161], v[240:243], v[8:11]
	v_mfma_f32_16x16x32_bf16 v[60:63], v[174:177], v[212:215], v[60:63]
	v_mfma_f32_16x16x32_bf16 v[52:55], v[204:207], v[212:215], v[52:55]
	v_mfma_f32_16x16x32_bf16 v[44:47], v[174:177], v[220:223], v[44:47]
	v_mfma_f32_16x16x32_bf16 v[36:39], v[204:207], v[220:223], v[36:39]
	v_mfma_f32_16x16x32_bf16 v[28:31], v[174:177], v[228:231], v[28:31]
	v_mfma_f32_16x16x32_bf16 v[20:23], v[204:207], v[228:231], v[20:23]
	v_mfma_f32_16x16x32_bf16 v[12:15], v[174:177], v[236:239], v[12:15]
	v_mfma_f32_16x16x32_bf16 v[4:7], v[204:207], v[236:239], v[4:7]
	v_mfma_f32_16x16x32_bf16 v[60:63], v[178:181], v[216:219], v[60:63]
	v_mfma_f32_16x16x32_bf16 v[52:55], v[208:211], v[216:219], v[52:55]
	v_mfma_f32_16x16x32_bf16 v[44:47], v[178:181], v[224:227], v[44:47]
	v_mfma_f32_16x16x32_bf16 v[36:39], v[208:211], v[224:227], v[36:39]
	v_mfma_f32_16x16x32_bf16 v[28:31], v[178:181], v[232:235], v[28:31]
	v_mfma_f32_16x16x32_bf16 v[20:23], v[208:211], v[232:235], v[20:23]
	v_mfma_f32_16x16x32_bf16 v[12:15], v[178:181], v[240:243], v[12:15]
	v_mfma_f32_16x16x32_bf16 v[4:7], v[208:211], v[240:243], v[4:7]
	s_setprio 3
	s_barrier
	s_add_i32 s60, s60, 2
	s_add_u32 s36, s36, 0x100
	s_addc_u32 s37, s37, 0
	s_add_u32 s58, s58, 0x100
	s_addc_u32 s59, s59, 0
	s_cmp_gt_u32 s60, 29
	s_cbranch_scc0 .LBB0_301
	s_branch .Lpost_p1
	.p2align 6
	s_nop 0
